# prologue p->bf16 loop unrolled with its eight 16-byte loads issued together
# baseline (speedup 1.0000x reference)
.LBB0_26:
	global_load_dwordx4 v[6:9], v[2:3], off
	v_lshl_add_u64 v[2:3], v[2:3], 0, s[4:5]
	global_load_dwordx4 v[10:13], v[2:3], off
	v_lshl_add_u64 v[2:3], v[2:3], 0, s[4:5]
	global_load_dwordx4 v[14:17], v[2:3], off
	v_lshl_add_u64 v[2:3], v[2:3], 0, s[4:5]
	global_load_dwordx4 v[18:21], v[2:3], off
	v_lshl_add_u64 v[2:3], v[2:3], 0, s[4:5]
	global_load_dwordx4 v[22:25], v[2:3], off
	v_lshl_add_u64 v[2:3], v[2:3], 0, s[4:5]
	global_load_dwordx4 v[26:29], v[2:3], off
	v_lshl_add_u64 v[2:3], v[2:3], 0, s[4:5]
	global_load_dwordx4 v[30:33], v[2:3], off
	v_lshl_add_u64 v[2:3], v[2:3], 0, s[4:5]
	global_load_dwordx4 v[34:37], v[2:3], off
	s_waitcnt vmcnt(7)
	v_cvt_pk_bf16_f32 v60, v6, v7
	v_cvt_pk_bf16_f32 v61, v8, v9
	global_store_dwordx2 v[4:5], v[60:61], off
	v_lshl_add_u64 v[4:5], v[4:5], 0, s[10:11]
	s_waitcnt vmcnt(7)
	v_cvt_pk_bf16_f32 v62, v10, v11
	v_cvt_pk_bf16_f32 v63, v12, v13
	global_store_dwordx2 v[4:5], v[62:63], off
	v_lshl_add_u64 v[4:5], v[4:5], 0, s[10:11]
	s_waitcnt vmcnt(7)
	v_cvt_pk_bf16_f32 v60, v14, v15
	v_cvt_pk_bf16_f32 v61, v16, v17
	global_store_dwordx2 v[4:5], v[60:61], off
	v_lshl_add_u64 v[4:5], v[4:5], 0, s[10:11]
	s_waitcnt vmcnt(7)
	v_cvt_pk_bf16_f32 v62, v18, v19
	v_cvt_pk_bf16_f32 v63, v20, v21
	global_store_dwordx2 v[4:5], v[62:63], off
	v_lshl_add_u64 v[4:5], v[4:5], 0, s[10:11]
	s_waitcnt vmcnt(7)
	v_cvt_pk_bf16_f32 v60, v22, v23
	v_cvt_pk_bf16_f32 v61, v24, v25
	global_store_dwordx2 v[4:5], v[60:61], off
	v_lshl_add_u64 v[4:5], v[4:5], 0, s[10:11]
	s_waitcnt vmcnt(7)
	v_cvt_pk_bf16_f32 v62, v26, v27
	v_cvt_pk_bf16_f32 v63, v28, v29
	global_store_dwordx2 v[4:5], v[62:63], off
	v_lshl_add_u64 v[4:5], v[4:5], 0, s[10:11]
	s_waitcnt vmcnt(7)
	v_cvt_pk_bf16_f32 v60, v30, v31
	v_cvt_pk_bf16_f32 v61, v32, v33
	global_store_dwordx2 v[4:5], v[60:61], off
	v_lshl_add_u64 v[4:5], v[4:5], 0, s[10:11]
	s_waitcnt vmcnt(7)
	v_cvt_pk_bf16_f32 v62, v34, v35
	v_cvt_pk_bf16_f32 v63, v36, v37
	global_store_dwordx2 v[4:5], v[62:63], off
